# stick-breaking unit split 3/5 between S5-chain owners and the others, on top of the batched S5 epilogue loads
# baseline (speedup 1.0000x reference)
; __global__ void __launch_bounds__(NWAVES * 64, 2) hybrid_fwd(Args args) {
;     ...
;             for (int o = vcu; o < 256; o += G) {
;                 const int s0 = (o < 128) ? 2 * o : 256 + 6 * (o - 128), ns = (o < 128) ? 2 : 6;
;                 for (int j = 0; j < ns; ++j) {
;                     const int su = s0 + j, bh = su >> 4, qb = su & 15, b = bh >> 3, h = bh & 7;
.LBB0_447:
	s_mov_b32 s53, s64
	s_cmpk_gt_i32 s43, 0x7f
	s_mov_b64 s[0:1], -1
	s_cbranch_scc0 .LBB0_449
	s_mul_i32 s0, s43, 5
	s_add_i32 s55, s0, 0xffffff00
	s_mov_b64 s[0:1], 0
.LBB0_449:
	s_mov_b32 s51, s65
	s_andn2_b64 vcc, exec, s[0:1]
	s_mov_b32 s64, 5
	s_cbranch_vccnz .LBB0_451
	s_mul_i32 s55, s43, 3
	s_mov_b32 s64, 3
